# grid barrier: unused per-XCD generation bump removed from the XCD leader path
# baseline (speedup 1.0000x reference)
; __device__ __forceinline__ unsigned xb_add(unsigned* p, unsigned v) { return __hip_atomic_fetch_add(p, v, __ATOMIC_RELAXED, __HIP_MEMORY_SCOPE_AGENT); }
; __device__ __forceinline__ void xcd_barrier(unsigned* bar, volatile LAS unsigned* st) {
;     ...
;       __builtin_amdgcn_fence(__ATOMIC_ACQUIRE, "agent");
;       xb_add(&bar[XB_XGEN(x)], 1u);
;       asm volatile("s_waitcnt vmcnt(0)" ::: "memory");
.LBB0_208:
	s_or_b64 exec, exec, s[0:1]
	s_mov_b64 s[0:1], exec
	v_mbcnt_lo_u32_b32 v0, s0, 0
	v_mbcnt_hi_u32_b32 v0, s1, v0
	v_cmp_eq_u32_e32 vcc, 0, v0
	s_waitcnt vmcnt(0)
	s_and_saveexec_b64 s[2:3], vcc
	s_cbranch_execz .LBB0_210
	s_bcnt1_i32_b64 s0, s[0:1]
	v_mov_b32_e32 v0, 0x2000
	v_mov_b32_e32 v1, s0
.LBB0_210:
	s_or_b64 exec, exec, s[2:3]
	buffer_inv sc1
	s_waitcnt vmcnt(0)

; __device__ __forceinline__ unsigned xb_add(unsigned* p, unsigned v) { return __hip_atomic_fetch_add(p, v, __ATOMIC_RELAXED, __HIP_MEMORY_SCOPE_AGENT); }
; __device__ __forceinline__ void xcd_barrier(unsigned* bar, volatile LAS unsigned* st) {
;     ...
;       __builtin_amdgcn_fence(__ATOMIC_ACQUIRE, "agent");
;       xb_add(&bar[XB_XGEN(x)], 1u);
;       asm volatile("s_waitcnt vmcnt(0)" ::: "memory");
.LBB0_276:
	s_or_b64 exec, exec, s[0:1]
	s_mov_b64 s[0:1], exec
	v_mbcnt_lo_u32_b32 v0, s0, 0
	v_mbcnt_hi_u32_b32 v0, s1, v0
	v_cmp_eq_u32_e32 vcc, 0, v0
	s_waitcnt vmcnt(0)
	s_and_saveexec_b64 s[2:3], vcc
	s_cbranch_execz .LBB0_278
	s_bcnt1_i32_b64 s0, s[0:1]
	v_mov_b32_e32 v0, 0x2000
	v_mov_b32_e32 v1, s0
.LBB0_278:
	s_or_b64 exec, exec, s[2:3]
	buffer_inv sc1
	s_waitcnt vmcnt(0)

; __device__ __forceinline__ unsigned xb_add(unsigned* p, unsigned v) { return __hip_atomic_fetch_add(p, v, __ATOMIC_RELAXED, __HIP_MEMORY_SCOPE_AGENT); }
; __device__ __forceinline__ void xcd_barrier(unsigned* bar, volatile LAS unsigned* st) {
;     ...
;       __builtin_amdgcn_fence(__ATOMIC_ACQUIRE, "agent");
;       xb_add(&bar[XB_XGEN(x)], 1u);
;       asm volatile("s_waitcnt vmcnt(0)" ::: "memory");
.LBB0_370:
	s_or_b64 exec, exec, s[0:1]
	s_mov_b64 s[0:1], exec
	v_mbcnt_lo_u32_b32 v0, s0, 0
	v_mbcnt_hi_u32_b32 v0, s1, v0
	v_cmp_eq_u32_e32 vcc, 0, v0
	s_waitcnt vmcnt(0)
	s_and_saveexec_b64 s[2:3], vcc
	s_cbranch_execz .LBB0_372
	s_bcnt1_i32_b64 s0, s[0:1]
	v_mov_b32_e32 v0, 0x2000
	v_mov_b32_e32 v1, s0
.LBB0_372:
	s_or_b64 exec, exec, s[2:3]
	buffer_inv sc1
	s_waitcnt vmcnt(0)

; __device__ __forceinline__ unsigned xb_add(unsigned* p, unsigned v) { return __hip_atomic_fetch_add(p, v, __ATOMIC_RELAXED, __HIP_MEMORY_SCOPE_AGENT); }
; __device__ __forceinline__ void xcd_barrier(unsigned* bar, volatile LAS unsigned* st) {
;     ...
;       __builtin_amdgcn_fence(__ATOMIC_ACQUIRE, "agent");
;       xb_add(&bar[XB_XGEN(x)], 1u);
;       asm volatile("s_waitcnt vmcnt(0)" ::: "memory");
.LBB0_458:
	s_or_b64 exec, exec, s[0:1]
	s_mov_b64 s[0:1], exec
	v_mbcnt_lo_u32_b32 v0, s0, 0
	v_mbcnt_hi_u32_b32 v0, s1, v0
	v_cmp_eq_u32_e32 vcc, 0, v0
	s_waitcnt vmcnt(0)
	s_and_saveexec_b64 s[2:3], vcc
	s_cbranch_execz .LBB0_460
	s_bcnt1_i32_b64 s0, s[0:1]
	v_mov_b32_e32 v0, 0x2000
	v_mov_b32_e32 v1, s0
.LBB0_460:
	s_or_b64 exec, exec, s[2:3]
	buffer_inv sc1
	s_waitcnt vmcnt(0)

; __device__ __forceinline__ unsigned xb_add(unsigned* p, unsigned v) { return __hip_atomic_fetch_add(p, v, __ATOMIC_RELAXED, __HIP_MEMORY_SCOPE_AGENT); }
; __device__ __forceinline__ void xcd_barrier(unsigned* bar, volatile LAS unsigned* st) {
;     ...
;       __builtin_amdgcn_fence(__ATOMIC_ACQUIRE, "agent");
;       xb_add(&bar[XB_XGEN(x)], 1u);
;       asm volatile("s_waitcnt vmcnt(0)" ::: "memory");
.LBB0_534:
	s_or_b64 exec, exec, s[0:1]
	s_mov_b64 s[0:1], exec
	v_mbcnt_lo_u32_b32 v0, s0, 0
	v_mbcnt_hi_u32_b32 v0, s1, v0
	v_cmp_eq_u32_e32 vcc, 0, v0
	s_waitcnt vmcnt(0)
	s_and_saveexec_b64 s[2:3], vcc
	s_cbranch_execz .LBB0_536
	s_bcnt1_i32_b64 s0, s[0:1]
	v_mov_b32_e32 v0, 0x2000
	v_mov_b32_e32 v1, s0
.LBB0_536:
	s_or_b64 exec, exec, s[2:3]
	buffer_inv sc1
	s_waitcnt vmcnt(0)

; __device__ __forceinline__ unsigned xb_add(unsigned* p, unsigned v) { return __hip_atomic_fetch_add(p, v, __ATOMIC_RELAXED, __HIP_MEMORY_SCOPE_AGENT); }
; __device__ __forceinline__ void xcd_barrier(unsigned* bar, volatile LAS unsigned* st) {
;     ...
;       __builtin_amdgcn_fence(__ATOMIC_ACQUIRE, "agent");
;       xb_add(&bar[XB_XGEN(x)], 1u);
;       asm volatile("s_waitcnt vmcnt(0)" ::: "memory");
.LBB0_796:
	s_or_b64 exec, exec, s[0:1]
	s_mov_b64 s[0:1], exec
	v_mbcnt_lo_u32_b32 v0, s0, 0
	v_mbcnt_hi_u32_b32 v0, s1, v0
	v_cmp_eq_u32_e32 vcc, 0, v0
	s_waitcnt vmcnt(0)
	s_and_saveexec_b64 s[2:3], vcc
	s_cbranch_execz .LBB0_798
	s_bcnt1_i32_b64 s0, s[0:1]
	v_mov_b32_e32 v0, 0x2000
	v_mov_b32_e32 v1, s0
.LBB0_798:
	s_or_b64 exec, exec, s[2:3]
	buffer_inv sc1
	s_waitcnt vmcnt(0)

; __device__ __forceinline__ unsigned xb_add(unsigned* p, unsigned v) { return __hip_atomic_fetch_add(p, v, __ATOMIC_RELAXED, __HIP_MEMORY_SCOPE_AGENT); }
; __device__ __forceinline__ void xcd_barrier(unsigned* bar, volatile LAS unsigned* st) {
;     ...
;       __builtin_amdgcn_fence(__ATOMIC_ACQUIRE, "agent");
;       xb_add(&bar[XB_XGEN(x)], 1u);
;       asm volatile("s_waitcnt vmcnt(0)" ::: "memory");
.LBB0_1227:
	s_or_b64 exec, exec, s[0:1]
	s_mov_b64 s[0:1], exec
	v_mbcnt_lo_u32_b32 v0, s0, 0
	v_mbcnt_hi_u32_b32 v0, s1, v0
	v_cmp_eq_u32_e32 vcc, 0, v0
	s_waitcnt vmcnt(0)
	s_and_saveexec_b64 s[2:3], vcc
	s_cbranch_execz .LBB0_1229
	s_bcnt1_i32_b64 s0, s[0:1]
	v_mov_b32_e32 v0, 0x2000
	v_mov_b32_e32 v1, s0
.LBB0_1229:
	s_or_b64 exec, exec, s[2:3]
	buffer_inv sc1
	s_waitcnt vmcnt(0)

; __device__ __forceinline__ unsigned xb_add(unsigned* p, unsigned v) { return __hip_atomic_fetch_add(p, v, __ATOMIC_RELAXED, __HIP_MEMORY_SCOPE_AGENT); }
; __device__ __forceinline__ void xcd_barrier(unsigned* bar, volatile LAS unsigned* st) {
;     ...
;       __builtin_amdgcn_fence(__ATOMIC_ACQUIRE, "agent");
;       xb_add(&bar[XB_XGEN(x)], 1u);
;       asm volatile("s_waitcnt vmcnt(0)" ::: "memory");
.LBB0_1318:
	s_or_b64 exec, exec, s[0:1]
	s_mov_b64 s[0:1], exec
	v_mbcnt_lo_u32_b32 v0, s0, 0
	v_mbcnt_hi_u32_b32 v0, s1, v0
	v_cmp_eq_u32_e32 vcc, 0, v0
	s_waitcnt vmcnt(0)
	s_and_saveexec_b64 s[2:3], vcc
	s_cbranch_execz .LBB0_1320
	s_bcnt1_i32_b64 s0, s[0:1]
	v_mov_b32_e32 v0, 0x2000
	v_mov_b32_e32 v1, s0
.LBB0_1320:
	s_or_b64 exec, exec, s[2:3]
	buffer_inv sc1
	s_waitcnt vmcnt(0)

; __device__ __forceinline__ unsigned xb_add(unsigned* p, unsigned v) { return __hip_atomic_fetch_add(p, v, __ATOMIC_RELAXED, __HIP_MEMORY_SCOPE_AGENT); }
; __device__ __forceinline__ void xcd_barrier(unsigned* bar, volatile LAS unsigned* st) {
;     ...
;       __builtin_amdgcn_fence(__ATOMIC_ACQUIRE, "agent");
;       xb_add(&bar[XB_XGEN(x)], 1u);
;       asm volatile("s_waitcnt vmcnt(0)" ::: "memory");
.LBB0_1414:
	s_or_b64 exec, exec, s[0:1]
	s_mov_b64 s[0:1], exec
	v_mbcnt_lo_u32_b32 v0, s0, 0
	v_mbcnt_hi_u32_b32 v0, s1, v0
	v_cmp_eq_u32_e32 vcc, 0, v0
	s_waitcnt vmcnt(0)
	s_and_saveexec_b64 s[2:3], vcc
	s_cbranch_execz .LBB0_1416
	s_bcnt1_i32_b64 s0, s[0:1]
	v_mov_b32_e32 v0, 0x2000
	v_mov_b32_e32 v1, s0
.LBB0_1416:
	s_or_b64 exec, exec, s[2:3]
	buffer_inv sc1
	s_waitcnt vmcnt(0)

; __device__ __forceinline__ unsigned xb_add(unsigned* p, unsigned v) { return __hip_atomic_fetch_add(p, v, __ATOMIC_RELAXED, __HIP_MEMORY_SCOPE_AGENT); }
; __device__ __forceinline__ void xcd_barrier(unsigned* bar, volatile LAS unsigned* st) {
;     ...
;       __builtin_amdgcn_fence(__ATOMIC_ACQUIRE, "agent");
;       xb_add(&bar[XB_XGEN(x)], 1u);
;       asm volatile("s_waitcnt vmcnt(0)" ::: "memory");
.LBB0_1500:
	s_or_b64 exec, exec, s[0:1]
	s_mov_b64 s[0:1], exec
	v_mbcnt_lo_u32_b32 v0, s0, 0
	v_mbcnt_hi_u32_b32 v0, s1, v0
	v_cmp_eq_u32_e32 vcc, 0, v0
	s_waitcnt vmcnt(0)
	s_and_saveexec_b64 s[2:3], vcc
	s_cbranch_execz .LBB0_1502
	s_bcnt1_i32_b64 s0, s[0:1]
	v_mov_b32_e32 v0, 0x2000
	v_mov_b32_e32 v1, s0
.LBB0_1502:
	s_or_b64 exec, exec, s[2:3]
	buffer_inv sc1
	s_waitcnt vmcnt(0)

; __device__ __forceinline__ unsigned xb_add(unsigned* p, unsigned v) { return __hip_atomic_fetch_add(p, v, __ATOMIC_RELAXED, __HIP_MEMORY_SCOPE_AGENT); }
; __device__ __forceinline__ void xcd_barrier(unsigned* bar, volatile LAS unsigned* st) {
;     ...
;       __builtin_amdgcn_fence(__ATOMIC_ACQUIRE, "agent");
;       xb_add(&bar[XB_XGEN(x)], 1u);
;       asm volatile("s_waitcnt vmcnt(0)" ::: "memory");
.LBB0_1576:
	s_or_b64 exec, exec, s[0:1]
	s_mov_b64 s[0:1], exec
	v_mbcnt_lo_u32_b32 v0, s0, 0
	v_mbcnt_hi_u32_b32 v0, s1, v0
	v_cmp_eq_u32_e32 vcc, 0, v0
	s_waitcnt vmcnt(0)
	s_and_saveexec_b64 s[2:3], vcc
	s_cbranch_execz .LBB0_1578
	s_bcnt1_i32_b64 s0, s[0:1]
	v_mov_b32_e32 v0, 0x2000
	v_mov_b32_e32 v1, s0
.LBB0_1578:
	s_or_b64 exec, exec, s[2:3]
	buffer_inv sc1
	s_waitcnt vmcnt(0)

; __device__ __forceinline__ unsigned xb_add(unsigned* p, unsigned v) { return __hip_atomic_fetch_add(p, v, __ATOMIC_RELAXED, __HIP_MEMORY_SCOPE_AGENT); }
; __device__ __forceinline__ void xcd_barrier(unsigned* bar, volatile LAS unsigned* st) {
;     ...
;       __builtin_amdgcn_fence(__ATOMIC_ACQUIRE, "agent");
;       xb_add(&bar[XB_XGEN(x)], 1u);
;       asm volatile("s_waitcnt vmcnt(0)" ::: "memory");
.LBB0_1670:
	s_or_b64 exec, exec, s[0:1]
	s_mov_b64 s[0:1], exec
	v_mbcnt_lo_u32_b32 v0, s0, 0
	v_mbcnt_hi_u32_b32 v0, s1, v0
	v_cmp_eq_u32_e32 vcc, 0, v0
	s_waitcnt vmcnt(0)
	s_and_saveexec_b64 s[2:3], vcc
	s_cbranch_execz .LBB0_1672
	s_bcnt1_i32_b64 s0, s[0:1]
	v_mov_b32_e32 v0, 0x2000
	v_mov_b32_e32 v1, s0
.LBB0_1672:
	s_or_b64 exec, exec, s[2:3]
	buffer_inv sc1
	s_waitcnt vmcnt(0)

; __device__ __forceinline__ unsigned xb_add(unsigned* p, unsigned v) { return __hip_atomic_fetch_add(p, v, __ATOMIC_RELAXED, __HIP_MEMORY_SCOPE_AGENT); }
; __device__ __forceinline__ void xcd_barrier(unsigned* bar, volatile LAS unsigned* st) {
;     ...
;       __builtin_amdgcn_fence(__ATOMIC_ACQUIRE, "agent");
;       xb_add(&bar[XB_XGEN(x)], 1u);
;       asm volatile("s_waitcnt vmcnt(0)" ::: "memory");
.LBB0_1758:
	s_or_b64 exec, exec, s[0:1]
	s_mov_b64 s[0:1], exec
	v_mbcnt_lo_u32_b32 v0, s0, 0
	v_mbcnt_hi_u32_b32 v0, s1, v0
	v_cmp_eq_u32_e32 vcc, 0, v0
	s_waitcnt vmcnt(0)
	s_and_saveexec_b64 s[2:3], vcc
	s_cbranch_execz .LBB0_1760
	s_bcnt1_i32_b64 s0, s[0:1]
	v_mov_b32_e32 v0, 0x2000
	v_mov_b32_e32 v1, s0
.LBB0_1760:
	s_or_b64 exec, exec, s[2:3]
	buffer_inv sc1
	s_waitcnt vmcnt(0)

; __device__ __forceinline__ unsigned xb_add(unsigned* p, unsigned v) { return __hip_atomic_fetch_add(p, v, __ATOMIC_RELAXED, __HIP_MEMORY_SCOPE_AGENT); }
; __device__ __forceinline__ void xcd_barrier(unsigned* bar, volatile LAS unsigned* st) {
;     ...
;       __builtin_amdgcn_fence(__ATOMIC_ACQUIRE, "agent");
;       xb_add(&bar[XB_XGEN(x)], 1u);
;       asm volatile("s_waitcnt vmcnt(0)" ::: "memory");
.LBB0_1834:
	s_or_b64 exec, exec, s[0:1]
	s_mov_b64 s[0:1], exec
	v_mbcnt_lo_u32_b32 v0, s0, 0
	v_mbcnt_hi_u32_b32 v0, s1, v0
	v_cmp_eq_u32_e32 vcc, 0, v0
	s_waitcnt vmcnt(0)
	s_and_saveexec_b64 s[2:3], vcc
	s_cbranch_execz .LBB0_1836
	s_bcnt1_i32_b64 s0, s[0:1]
	v_mov_b32_e32 v0, 0x2000
	v_mov_b32_e32 v1, s0
.LBB0_1836:
	s_or_b64 exec, exec, s[2:3]
	buffer_inv sc1
	s_waitcnt vmcnt(0)

; __device__ __forceinline__ unsigned xb_add(unsigned* p, unsigned v) { return __hip_atomic_fetch_add(p, v, __ATOMIC_RELAXED, __HIP_MEMORY_SCOPE_AGENT); }
; __device__ __forceinline__ void xcd_barrier(unsigned* bar, volatile LAS unsigned* st) {
;     ...
;       __builtin_amdgcn_fence(__ATOMIC_ACQUIRE, "agent");
;       xb_add(&bar[XB_XGEN(x)], 1u);
;       asm volatile("s_waitcnt vmcnt(0)" ::: "memory");
.LBB0_1928:
	s_or_b64 exec, exec, s[0:1]
	s_mov_b64 s[0:1], exec
	v_mbcnt_lo_u32_b32 v0, s0, 0
	v_mbcnt_hi_u32_b32 v0, s1, v0
	v_cmp_eq_u32_e32 vcc, 0, v0
	s_waitcnt vmcnt(0)
	s_and_saveexec_b64 s[2:3], vcc
	s_cbranch_execz .LBB0_1930
	s_bcnt1_i32_b64 s0, s[0:1]
	v_mov_b32_e32 v0, 0x2000
	v_mov_b32_e32 v1, s0
.LBB0_1930:
	s_or_b64 exec, exec, s[2:3]
	buffer_inv sc1
	s_waitcnt vmcnt(0)

; __device__ __forceinline__ unsigned xb_add(unsigned* p, unsigned v) { return __hip_atomic_fetch_add(p, v, __ATOMIC_RELAXED, __HIP_MEMORY_SCOPE_AGENT); }
; __device__ __forceinline__ void xcd_barrier(unsigned* bar, volatile LAS unsigned* st) {
;     ...
;       __builtin_amdgcn_fence(__ATOMIC_ACQUIRE, "agent");
;       xb_add(&bar[XB_XGEN(x)], 1u);
;       asm volatile("s_waitcnt vmcnt(0)" ::: "memory");
.LBB0_2016:
	s_or_b64 exec, exec, s[0:1]
	s_mov_b64 s[0:1], exec
	v_mbcnt_lo_u32_b32 v0, s0, 0
	v_mbcnt_hi_u32_b32 v0, s1, v0
	v_cmp_eq_u32_e32 vcc, 0, v0
	s_waitcnt vmcnt(0)
	s_and_saveexec_b64 s[2:3], vcc
	s_cbranch_execz .LBB0_2018
	s_bcnt1_i32_b64 s0, s[0:1]
	v_mov_b32_e32 v0, 0x2000
	v_mov_b32_e32 v1, s0
.LBB0_2018:
	s_or_b64 exec, exec, s[2:3]
	buffer_inv sc1
	s_waitcnt vmcnt(0)

; __device__ __forceinline__ unsigned xb_add(unsigned* p, unsigned v) { return __hip_atomic_fetch_add(p, v, __ATOMIC_RELAXED, __HIP_MEMORY_SCOPE_AGENT); }
; __device__ __forceinline__ void xcd_barrier(unsigned* bar, volatile LAS unsigned* st) {
;     ...
;       __builtin_amdgcn_fence(__ATOMIC_ACQUIRE, "agent");
;       xb_add(&bar[XB_XGEN(x)], 1u);
;       asm volatile("s_waitcnt vmcnt(0)" ::: "memory");
.LBB0_2092:
	s_or_b64 exec, exec, s[0:1]
	s_mov_b64 s[0:1], exec
	v_mbcnt_lo_u32_b32 v0, s0, 0
	v_mbcnt_hi_u32_b32 v0, s1, v0
	v_cmp_eq_u32_e32 vcc, 0, v0
	s_waitcnt vmcnt(0)
	s_and_saveexec_b64 s[2:3], vcc
	s_cbranch_execz .LBB0_2094
	s_bcnt1_i32_b64 s0, s[0:1]
	v_mov_b32_e32 v0, 0x2000
	v_mov_b32_e32 v1, s0
.LBB0_2094:
	s_or_b64 exec, exec, s[2:3]
	buffer_inv sc1
	s_waitcnt vmcnt(0)

; __device__ __forceinline__ unsigned xb_add(unsigned* p, unsigned v) { return __hip_atomic_fetch_add(p, v, __ATOMIC_RELAXED, __HIP_MEMORY_SCOPE_AGENT); }
; __device__ __forceinline__ void xcd_barrier(unsigned* bar, volatile LAS unsigned* st) {
;     ...
;       __builtin_amdgcn_fence(__ATOMIC_ACQUIRE, "agent");
;       xb_add(&bar[XB_XGEN(x)], 1u);
;       asm volatile("s_waitcnt vmcnt(0)" ::: "memory");
.LBB0_2192:
	s_or_b64 exec, exec, s[0:1]
	s_mov_b64 s[0:1], exec
	v_mbcnt_lo_u32_b32 v0, s0, 0
	v_mbcnt_hi_u32_b32 v0, s1, v0
	v_cmp_eq_u32_e32 vcc, 0, v0
	s_waitcnt vmcnt(0)
	s_and_saveexec_b64 s[2:3], vcc
	s_cbranch_execz .LBB0_2194
	s_bcnt1_i32_b64 s0, s[0:1]
	v_mov_b32_e32 v0, 0x2000
	v_mov_b32_e32 v1, s0
.LBB0_2194:
	s_or_b64 exec, exec, s[2:3]
	buffer_inv sc1
	s_waitcnt vmcnt(0)

; __device__ __forceinline__ unsigned xb_add(unsigned* p, unsigned v) { return __hip_atomic_fetch_add(p, v, __ATOMIC_RELAXED, __HIP_MEMORY_SCOPE_AGENT); }
; __device__ __forceinline__ void xcd_barrier(unsigned* bar, volatile LAS unsigned* st) {
;     ...
;       __builtin_amdgcn_fence(__ATOMIC_ACQUIRE, "agent");
;       xb_add(&bar[XB_XGEN(x)], 1u);
;       asm volatile("s_waitcnt vmcnt(0)" ::: "memory");
.LBB0_2271:
	s_or_b64 exec, exec, s[0:1]
	s_mov_b64 s[0:1], exec
	v_mbcnt_lo_u32_b32 v0, s0, 0
	v_mbcnt_hi_u32_b32 v0, s1, v0
	v_cmp_eq_u32_e32 vcc, 0, v0
	s_waitcnt vmcnt(0)
	s_and_saveexec_b64 s[2:3], vcc
	s_cbranch_execz .LBB0_2273
	s_bcnt1_i32_b64 s0, s[0:1]
	v_mov_b32_e32 v0, 0x2000
	v_mov_b32_e32 v1, s0
.LBB0_2273:
	s_or_b64 exec, exec, s[2:3]
	buffer_inv sc1
	s_waitcnt vmcnt(0)

; __device__ __forceinline__ unsigned xb_add(unsigned* p, unsigned v) { return __hip_atomic_fetch_add(p, v, __ATOMIC_RELAXED, __HIP_MEMORY_SCOPE_AGENT); }
; __device__ __forceinline__ void xcd_barrier(unsigned* bar, volatile LAS unsigned* st) {
;     ...
;       __builtin_amdgcn_fence(__ATOMIC_ACQUIRE, "agent");
;       xb_add(&bar[XB_XGEN(x)], 1u);
;       asm volatile("s_waitcnt vmcnt(0)" ::: "memory");
.LBB0_2359:
	s_or_b64 exec, exec, s[0:1]
	s_mov_b64 s[0:1], exec
	v_mbcnt_lo_u32_b32 v0, s0, 0
	v_mbcnt_hi_u32_b32 v0, s1, v0
	v_cmp_eq_u32_e32 vcc, 0, v0
	s_waitcnt vmcnt(0)
	s_and_saveexec_b64 s[2:3], vcc
	s_cbranch_execz .LBB0_2361
	s_bcnt1_i32_b64 s0, s[0:1]
	v_mov_b32_e32 v0, 0x2000
	v_mov_b32_e32 v1, s0
.LBB0_2361:
	s_or_b64 exec, exec, s[2:3]
	buffer_inv sc1
	s_waitcnt vmcnt(0)

; __device__ __forceinline__ unsigned xb_add(unsigned* p, unsigned v) { return __hip_atomic_fetch_add(p, v, __ATOMIC_RELAXED, __HIP_MEMORY_SCOPE_AGENT); }
; __device__ __forceinline__ void xcd_barrier(unsigned* bar, volatile LAS unsigned* st) {
;     ...
;       __builtin_amdgcn_fence(__ATOMIC_ACQUIRE, "agent");
;       xb_add(&bar[XB_XGEN(x)], 1u);
;       asm volatile("s_waitcnt vmcnt(0)" ::: "memory");
.LBB0_2417:
	s_or_b64 exec, exec, s[0:1]
	s_mov_b64 s[0:1], exec
	v_mbcnt_lo_u32_b32 v0, s0, 0
	v_mbcnt_hi_u32_b32 v0, s1, v0
	v_cmp_eq_u32_e32 vcc, 0, v0
	s_waitcnt vmcnt(0)
	s_and_saveexec_b64 s[2:3], vcc
	s_cbranch_execz .LBB0_2419
	s_bcnt1_i32_b64 s0, s[0:1]
	v_mov_b32_e32 v0, 0x2000
	v_mov_b32_e32 v1, s0
.LBB0_2419:
	s_or_b64 exec, exec, s[2:3]
	buffer_inv sc1
	s_waitcnt vmcnt(0)

; __device__ __forceinline__ unsigned xb_add(unsigned* p, unsigned v) { return __hip_atomic_fetch_add(p, v, __ATOMIC_RELAXED, __HIP_MEMORY_SCOPE_AGENT); }
; __device__ __forceinline__ void xcd_barrier(unsigned* bar, volatile LAS unsigned* st) {
;     ...
;       __builtin_amdgcn_fence(__ATOMIC_ACQUIRE, "agent");
;       xb_add(&bar[XB_XGEN(x)], 1u);
;       asm volatile("s_waitcnt vmcnt(0)" ::: "memory");
.LBB0_2499:
	s_or_b64 exec, exec, s[0:1]
	s_mov_b64 s[0:1], exec
	v_mbcnt_lo_u32_b32 v0, s0, 0
	v_mbcnt_hi_u32_b32 v0, s1, v0
	v_cmp_eq_u32_e32 vcc, 0, v0
	s_waitcnt vmcnt(0)
	s_and_saveexec_b64 s[2:3], vcc
	s_cbranch_execz .LBB0_2501
	s_bcnt1_i32_b64 s0, s[0:1]
	v_mov_b32_e32 v0, 0x2000
	v_mov_b32_e32 v1, s0
.LBB0_2501:
	s_or_b64 exec, exec, s[2:3]
	buffer_inv sc1
	s_waitcnt vmcnt(0)

; __device__ __forceinline__ unsigned xb_add(unsigned* p, unsigned v) { return __hip_atomic_fetch_add(p, v, __ATOMIC_RELAXED, __HIP_MEMORY_SCOPE_AGENT); }
; __device__ __forceinline__ void xcd_barrier(unsigned* bar, volatile LAS unsigned* st) {
;     ...
;       __builtin_amdgcn_fence(__ATOMIC_ACQUIRE, "agent");
;       xb_add(&bar[XB_XGEN(x)], 1u);
;       asm volatile("s_waitcnt vmcnt(0)" ::: "memory");
.LBB0_2565:
	s_or_b64 exec, exec, s[0:1]
	s_mov_b64 s[0:1], exec
	v_mbcnt_lo_u32_b32 v0, s0, 0
	v_mbcnt_hi_u32_b32 v0, s1, v0
	v_cmp_eq_u32_e32 vcc, 0, v0
	s_waitcnt vmcnt(0)
	s_and_saveexec_b64 s[2:3], vcc
	s_cbranch_execz .LBB0_2567
	s_bcnt1_i32_b64 s0, s[0:1]
	v_mov_b32_e32 v0, 0x2000
	v_mov_b32_e32 v1, s0
.LBB0_2567:
	s_or_b64 exec, exec, s[2:3]
	buffer_inv sc1
	s_waitcnt vmcnt(0)

; __device__ __forceinline__ unsigned xb_add(unsigned* p, unsigned v) { return __hip_atomic_fetch_add(p, v, __ATOMIC_RELAXED, __HIP_MEMORY_SCOPE_AGENT); }
; __device__ __forceinline__ void xcd_barrier(unsigned* bar, volatile LAS unsigned* st) {
;     ...
;       __builtin_amdgcn_fence(__ATOMIC_ACQUIRE, "agent");
;       xb_add(&bar[XB_XGEN(x)], 1u);
;       asm volatile("s_waitcnt vmcnt(0)" ::: "memory");
.LBB0_2659:
	s_or_b64 exec, exec, s[0:1]
	s_mov_b64 s[0:1], exec
	v_mbcnt_lo_u32_b32 v0, s0, 0
	v_mbcnt_hi_u32_b32 v0, s1, v0
	v_cmp_eq_u32_e32 vcc, 0, v0
	s_waitcnt vmcnt(0)
	s_and_saveexec_b64 s[2:3], vcc
	s_cbranch_execz .LBB0_2661
	s_bcnt1_i32_b64 s0, s[0:1]
	v_mov_b32_e32 v0, 0x2000
	v_mov_b32_e32 v1, s0
.LBB0_2661:
	s_or_b64 exec, exec, s[2:3]
	buffer_inv sc1
	s_waitcnt vmcnt(0)

; __device__ __forceinline__ unsigned xb_add(unsigned* p, unsigned v) { return __hip_atomic_fetch_add(p, v, __ATOMIC_RELAXED, __HIP_MEMORY_SCOPE_AGENT); }
; __device__ __forceinline__ void xcd_barrier(unsigned* bar, volatile LAS unsigned* st) {
;     ...
;       __builtin_amdgcn_fence(__ATOMIC_ACQUIRE, "agent");
;       xb_add(&bar[XB_XGEN(x)], 1u);
;       asm volatile("s_waitcnt vmcnt(0)" ::: "memory");
.LBB0_2749:
	s_or_b64 exec, exec, s[0:1]
	s_mov_b64 s[0:1], exec
	v_mbcnt_lo_u32_b32 v0, s0, 0
	v_mbcnt_hi_u32_b32 v0, s1, v0
	v_cmp_eq_u32_e32 vcc, 0, v0
	s_waitcnt vmcnt(0)
	s_and_saveexec_b64 s[2:3], vcc
	s_cbranch_execz .LBB0_2751
	s_bcnt1_i32_b64 s0, s[0:1]
	v_mov_b32_e32 v0, 0x2000
	v_mov_b32_e32 v1, s0
.LBB0_2751:
	s_or_b64 exec, exec, s[2:3]
	buffer_inv sc1
	s_waitcnt vmcnt(0)
